# P7 Hyena: waves 4-7 delayed by s_sleep 4 at the start of each product (de-phase the two waves of a SIMD)
# baseline (speedup 1.0000x reference)
.LBB0_2203:
	s_or_b64 exec, exec, s[16:17]
	s_add_i32 s20, s12, 0x200
	s_ashr_i32 s20, s20, 3
	s_ashr_i32 s21, s20, 31
	s_lshl_b64 s[20:21], s[20:21], 7
	s_and_b32 s32, s12, 7
	v_mov_b32_e32 v244, s32
	v_or3_b32 v244, s20, v140, v244
	v_mov_b32_e32 v245, s21
	v_lshlrev_b64 v[244:245], 12, v[244:245]
	v_lshl_add_u64 v[244:245], v[160:161], 0, v[244:245]
	global_load_dword v233, v[244:245], off
	global_load_dword v233, v[244:245], off offset:64
	global_load_dword v233, v[244:245], off offset:128
	global_load_dword v233, v[244:245], off offset:192
	global_load_dword v233, v[244:245], off offset:256
	global_load_dword v233, v[244:245], off offset:320
	global_load_dword v233, v[244:245], off offset:384
	global_load_dword v233, v[244:245], off offset:448
	global_load_dword v233, v[244:245], off offset:512
	global_load_dword v233, v[244:245], off offset:576
	global_load_dword v233, v[244:245], off offset:640
	global_load_dword v233, v[244:245], off offset:704
	global_load_dword v233, v[244:245], off offset:768
	global_load_dword v233, v[244:245], off offset:832
	global_load_dword v233, v[244:245], off offset:896
	global_load_dword v233, v[244:245], off offset:960
	s_cmp_lt_u32 s88, 4
	s_cbranch_scc1 .Lp7_nostag0
	s_sleep 4
.Lp7_nostag0:
	ds_read2_b32 v[6:7], v179 offset1:1
	ds_read2_b32 v[10:11], v178 offset1:1
	ds_read2_b32 v[18:19], v177 offset1:1
	ds_read2_b32 v[14:15], v181 offset1:1
	ds_read2_b32 v[16:17], v182 offset1:1
	s_waitcnt lgkmcnt(0)
	v_alignbit_b32 v13, v7, v6, v3
	v_alignbit_b32 v12, v6, v11, v4
	ds_read_b128 v[6:9], v5 offset:896
	v_alignbit_b32 v11, v11, v19, v1
	v_alignbit_b32 v10, v10, v18, v2
	ds_read_b128 v[78:81], v5
	ds_read_b128 v[70:73], v5 offset:64
	ds_read2_b32 v[18:19], v183 offset1:1
	v_add_u32_e32 v20, 0xcd4, v141
	v_add_u32_e32 v21, 0xcdc, v141
	ds_read2_b32 v[24:25], v184 offset1:1
	ds_read2_b32 v[26:27], v20 offset1:1
	ds_read2_b32 v[28:29], v21 offset1:1
	v_alignbit_b32 v16, v16, v14, v2
	s_waitcnt lgkmcnt(0)
	v_alignbit_b32 v19, v19, v18, v3
	v_alignbit_b32 v18, v18, v17, v4
	v_alignbit_b32 v17, v17, v15, v1
	v_mfma_f32_16x16x32_bf16 v[10:13], v[10:13], v[78:81], 0
	v_alignbit_b32 v15, v27, v25, v1
	v_alignbit_b32 v14, v26, v24, v2
	ds_read_b128 v[54:57], v5 offset:128
	v_mfma_f32_16x16x32_bf16 v[20:23], v[16:19], v[78:81], 0
	v_add_u32_e32 v30, 0xd1c, v141
	v_add_u32_e32 v98, 0xedc, v141
	v_add_u32_e32 v130, 0xfdc, v141
	v_mfma_f32_16x16x32_bf16 v[10:13], v[16:19], v[70:73], v[10:13]
	v_alignbit_b32 v17, v29, v28, v3
	v_alignbit_b32 v16, v28, v27, v4
	v_add_u32_e32 v28, 0xd14, v141
	s_mov_b32 s2, -16
	v_mfma_f32_16x16x32_bf16 v[18:21], v[14:17], v[70:73], v[20:23]
	s_nop 2
	v_add_u32_e32 v22, 0xd10, v141
	ds_read2_b32 v[22:23], v22 offset1:1
	ds_read2_b32 v[28:29], v28 offset1:1
	ds_read2_b32 v[30:31], v30 offset1:1
	ds_read_b128 v[58:61], v5 offset:192
	v_mfma_f32_16x16x32_bf16 v[24:27], v[14:17], v[78:81], 0
	s_waitcnt lgkmcnt(0)
	v_mfma_f32_16x16x32_bf16 v[10:13], v[14:17], v[54:57], v[10:13]
	v_add_u32_e32 v14, 0xd50, v141
	ds_read2_b32 v[32:33], v14 offset1:1
	v_alignbit_b32 v17, v31, v30, v3
	v_alignbit_b32 v16, v30, v29, v4
	v_alignbit_b32 v15, v29, v23, v1
	v_alignbit_b32 v14, v28, v22, v2
	s_nop 1
	v_mfma_f32_16x16x32_bf16 v[28:31], v[14:17], v[78:81], 0
	v_mfma_f32_16x16x32_bf16 v[22:25], v[14:17], v[70:73], v[24:27]
	v_mfma_f32_16x16x32_bf16 v[18:21], v[14:17], v[54:57], v[18:21]
	s_nop 1
	v_add_u32_e32 v26, 0xd90, v141
	v_add_u32_e32 v27, 0xd94, v141
	v_mfma_f32_16x16x32_bf16 v[10:13], v[14:17], v[58:61], v[10:13]
	v_add_u32_e32 v14, 0xd54, v141
	v_add_u32_e32 v16, 0xd5c, v141
	ds_read2_b32 v[14:15], v14 offset1:1
	ds_read2_b32 v[16:17], v16 offset1:1
	ds_read2_b32 v[36:37], v26 offset1:1
	ds_read2_b32 v[38:39], v27 offset1:1
	ds_read_b128 v[46:49], v5 offset:256
	ds_read_b128 v[42:45], v5 offset:320
	s_waitcnt lgkmcnt(0)
	v_alignbit_b32 v14, v14, v32, v2
	v_alignbit_b32 v17, v17, v16, v3
	v_alignbit_b32 v16, v16, v15, v4
	v_alignbit_b32 v15, v15, v33, v1
	s_nop 1
	v_mfma_f32_16x16x32_bf16 v[32:35], v[14:17], v[78:81], 0
	v_mfma_f32_16x16x32_bf16 v[26:29], v[14:17], v[70:73], v[28:31]
	v_mfma_f32_16x16x32_bf16 v[22:25], v[14:17], v[54:57], v[22:25]
	s_nop 1
	v_add_u32_e32 v30, 0xddc, v141
	v_mfma_f32_16x16x32_bf16 v[18:21], v[14:17], v[58:61], v[18:21]
	v_mfma_f32_16x16x32_bf16 v[10:13], v[14:17], v[46:49], v[10:13]
	v_add_u32_e32 v14, 0xd9c, v141
	ds_read2_b32 v[14:15], v14 offset1:1
	v_add_u32_e32 v16, 0xdd0, v141
	v_add_u32_e32 v17, 0xdd4, v141
	ds_read2_b32 v[40:41], v16 offset1:1
	ds_read2_b32 v[50:51], v17 offset1:1
	ds_read2_b32 v[52:53], v30 offset1:1
	s_waitcnt lgkmcnt(0)
	v_alignbit_b32 v17, v15, v14, v3
	v_alignbit_b32 v16, v14, v39, v4
	v_alignbit_b32 v15, v39, v37, v1
	v_alignbit_b32 v14, v38, v36, v2
	s_nop 1
	v_mfma_f32_16x16x32_bf16 v[36:39], v[14:17], v[78:81], 0
	v_mfma_f32_16x16x32_bf16 v[30:33], v[14:17], v[70:73], v[32:35]
	v_mfma_f32_16x16x32_bf16 v[26:29], v[14:17], v[54:57], v[26:29]
	v_mfma_f32_16x16x32_bf16 v[22:25], v[14:17], v[58:61], v[22:25]
	v_mfma_f32_16x16x32_bf16 v[18:21], v[14:17], v[46:49], v[18:21]
	v_mfma_f32_16x16x32_bf16 v[10:13], v[14:17], v[42:45], v[10:13]
	v_alignbit_b32 v17, v53, v52, v3
	v_alignbit_b32 v16, v52, v51, v4
	v_alignbit_b32 v15, v51, v41, v1
	v_alignbit_b32 v14, v50, v40, v2
	v_add_u32_e32 v40, 0xe1c, v141
	s_nop 0
	v_mfma_f32_16x16x32_bf16 v[62:65], v[14:17], v[58:61], v[26:29]
	s_nop 2
	ds_read_b128 v[26:29], v5 offset:384
	v_mfma_f32_16x16x32_bf16 v[34:37], v[14:17], v[70:73], v[36:39]
	s_nop 2
	v_add_u32_e32 v38, 0xe10, v141
	v_add_u32_e32 v39, 0xe14, v141
	ds_read2_b32 v[66:67], v38 offset1:1
	ds_read2_b32 v[68:69], v39 offset1:1
	ds_read2_b32 v[74:75], v40 offset1:1
	ds_read_b128 v[38:41], v5 offset:448
	v_mfma_f32_16x16x32_bf16 v[50:53], v[14:17], v[78:81], 0
	v_mfma_f32_16x16x32_bf16 v[30:33], v[14:17], v[54:57], v[30:33]
	v_mfma_f32_16x16x32_bf16 v[22:25], v[14:17], v[46:49], v[22:25]
	v_mfma_f32_16x16x32_bf16 v[18:21], v[14:17], v[42:45], v[18:21]
	s_waitcnt lgkmcnt(0)
	v_mfma_f32_16x16x32_bf16 v[10:13], v[14:17], v[26:29], v[10:13]
	v_add_u32_e32 v14, 0xe50, v141
	ds_read2_b32 v[76:77], v14 offset1:1
	v_alignbit_b32 v17, v75, v74, v3
	v_alignbit_b32 v16, v74, v69, v4
	v_alignbit_b32 v15, v69, v67, v1
	v_alignbit_b32 v14, v68, v66, v2
	v_add_u32_e32 v74, 0xe90, v141
	v_add_u32_e32 v75, 0xe94, v141
	v_mfma_f32_16x16x32_bf16 v[66:69], v[14:17], v[78:81], 0
	v_mfma_f32_16x16x32_bf16 v[50:53], v[14:17], v[70:73], v[50:53]
	v_mfma_f32_16x16x32_bf16 v[34:37], v[14:17], v[54:57], v[34:37]
	v_mfma_f32_16x16x32_bf16 v[30:33], v[14:17], v[58:61], v[30:33]
	v_mfma_f32_16x16x32_bf16 v[62:65], v[14:17], v[46:49], v[62:65]
	v_mfma_f32_16x16x32_bf16 v[22:25], v[14:17], v[42:45], v[22:25]
	v_mfma_f32_16x16x32_bf16 v[18:21], v[14:17], v[26:29], v[18:21]
	v_mfma_f32_16x16x32_bf16 v[10:13], v[14:17], v[38:41], v[10:13]
	v_add_u32_e32 v14, 0xe54, v141
	v_add_u32_e32 v16, 0xe5c, v141
	ds_read2_b32 v[14:15], v14 offset1:1
	ds_read2_b32 v[16:17], v16 offset1:1
	ds_read2_b32 v[90:91], v74 offset1:1
	ds_read2_b32 v[92:93], v75 offset1:1
	s_waitcnt lgkmcnt(0)
	v_alignbit_b32 v14, v14, v76, v2
	v_alignbit_b32 v17, v17, v16, v3
	v_alignbit_b32 v16, v16, v15, v4
	v_alignbit_b32 v15, v15, v77, v1
	s_nop 1
	v_mfma_f32_16x16x32_bf16 v[82:85], v[14:17], v[58:61], v[34:37]
	v_mfma_f32_16x16x32_bf16 v[86:89], v[14:17], v[46:49], v[30:33]
	s_nop 2
	ds_read_b128 v[30:33], v5 offset:512
	ds_read_b128 v[34:37], v5 offset:576
	v_mfma_f32_16x16x32_bf16 v[74:77], v[14:17], v[78:81], 0
	v_mfma_f32_16x16x32_bf16 v[66:69], v[14:17], v[70:73], v[66:69]
	v_mfma_f32_16x16x32_bf16 v[50:53], v[14:17], v[54:57], v[50:53]
	v_mfma_f32_16x16x32_bf16 v[62:65], v[14:17], v[42:45], v[62:65]
	v_mfma_f32_16x16x32_bf16 v[22:25], v[14:17], v[26:29], v[22:25]
	v_mfma_f32_16x16x32_bf16 v[18:21], v[14:17], v[38:41], v[18:21]
	s_waitcnt lgkmcnt(0)
	v_mfma_f32_16x16x32_bf16 v[10:13], v[14:17], v[30:33], v[10:13]
	v_add_u32_e32 v14, 0xe9c, v141
	ds_read2_b32 v[14:15], v14 offset1:1
	v_add_u32_e32 v16, 0xed0, v141
	v_add_u32_e32 v17, 0xed4, v141
	ds_read2_b32 v[94:95], v16 offset1:1
	ds_read2_b32 v[96:97], v17 offset1:1
	ds_read2_b32 v[98:99], v98 offset1:1
	s_waitcnt lgkmcnt(0)
	v_alignbit_b32 v17, v15, v14, v3
	v_alignbit_b32 v16, v14, v93, v4
	v_alignbit_b32 v15, v93, v91, v1
	v_alignbit_b32 v14, v92, v90, v2
	s_nop 1
	v_mfma_f32_16x16x32_bf16 v[90:93], v[14:17], v[78:81], 0
	v_mfma_f32_16x16x32_bf16 v[74:77], v[14:17], v[70:73], v[74:77]
	v_mfma_f32_16x16x32_bf16 v[66:69], v[14:17], v[54:57], v[66:69]
	v_mfma_f32_16x16x32_bf16 v[50:53], v[14:17], v[58:61], v[50:53]
	v_mfma_f32_16x16x32_bf16 v[82:85], v[14:17], v[46:49], v[82:85]
	v_mfma_f32_16x16x32_bf16 v[86:89], v[14:17], v[42:45], v[86:89]
	v_mfma_f32_16x16x32_bf16 v[62:65], v[14:17], v[26:29], v[62:65]
	v_mfma_f32_16x16x32_bf16 v[22:25], v[14:17], v[38:41], v[22:25]
	v_mfma_f32_16x16x32_bf16 v[18:21], v[14:17], v[30:33], v[18:21]
	v_mfma_f32_16x16x32_bf16 v[10:13], v[14:17], v[34:37], v[10:13]
	v_alignbit_b32 v17, v99, v98, v3
	v_alignbit_b32 v16, v98, v97, v4
	v_alignbit_b32 v15, v97, v95, v1
	v_alignbit_b32 v14, v96, v94, v2
	s_nop 1
	v_mfma_f32_16x16x32_bf16 v[98:101], v[14:17], v[30:33], v[22:25]
	s_nop 2
	ds_read_b128 v[22:25], v5 offset:640
	v_mfma_f32_16x16x32_bf16 v[102:105], v[14:17], v[34:37], v[18:21]
	s_nop 2
	v_add_u32_e32 v18, 0xf10, v141
	v_add_u32_e32 v19, 0xf14, v141
	v_add_u32_e32 v20, 0xf1c, v141
	ds_read2_b32 v[106:107], v18 offset1:1
	ds_read2_b32 v[108:109], v19 offset1:1
	ds_read2_b32 v[110:111], v20 offset1:1
	ds_read_b128 v[18:21], v5 offset:704
	v_mfma_f32_16x16x32_bf16 v[94:97], v[14:17], v[78:81], 0
	v_mfma_f32_16x16x32_bf16 v[90:93], v[14:17], v[70:73], v[90:93]
	v_mfma_f32_16x16x32_bf16 v[74:77], v[14:17], v[54:57], v[74:77]
	v_mfma_f32_16x16x32_bf16 v[66:69], v[14:17], v[58:61], v[66:69]
	v_mfma_f32_16x16x32_bf16 v[50:53], v[14:17], v[46:49], v[50:53]
	v_mfma_f32_16x16x32_bf16 v[82:85], v[14:17], v[42:45], v[82:85]
	v_mfma_f32_16x16x32_bf16 v[86:89], v[14:17], v[26:29], v[86:89]
	v_mfma_f32_16x16x32_bf16 v[62:65], v[14:17], v[38:41], v[62:65]
	s_waitcnt lgkmcnt(0)
	v_mfma_f32_16x16x32_bf16 v[10:13], v[14:17], v[22:25], v[10:13]
	v_add_u32_e32 v14, 0xf50, v141
	ds_read2_b32 v[114:115], v14 offset1:1
	v_alignbit_b32 v17, v111, v110, v3
	v_alignbit_b32 v16, v110, v109, v4
	v_alignbit_b32 v15, v109, v107, v1
	v_alignbit_b32 v14, v108, v106, v2
	s_nop 1
	v_mfma_f32_16x16x32_bf16 v[110:113], v[14:17], v[18:21], v[10:13]
	s_nop 2
	v_add_u32_e32 v10, 0xf54, v141
	v_add_u32_e32 v12, 0xf5c, v141
	ds_read2_b32 v[10:11], v10 offset1:1
	ds_read2_b32 v[12:13], v12 offset1:1
	v_mfma_f32_16x16x32_bf16 v[106:109], v[14:17], v[78:81], 0
	s_waitcnt lgkmcnt(0)
	v_alignbit_b32 v115, v11, v115, v1
	v_mfma_f32_16x16x32_bf16 v[94:97], v[14:17], v[70:73], v[94:97]
	v_alignbit_b32 v117, v13, v12, v3
	v_alignbit_b32 v116, v12, v11, v4
	v_alignbit_b32 v114, v10, v114, v2
	v_mfma_f32_16x16x32_bf16 v[90:93], v[14:17], v[54:57], v[90:93]
	v_mfma_f32_16x16x32_bf16 v[74:77], v[14:17], v[58:61], v[74:77]
	v_mfma_f32_16x16x32_bf16 v[66:69], v[14:17], v[46:49], v[66:69]
	v_mfma_f32_16x16x32_bf16 v[50:53], v[14:17], v[42:45], v[50:53]
	v_mfma_f32_16x16x32_bf16 v[82:85], v[14:17], v[26:29], v[82:85]
	v_mfma_f32_16x16x32_bf16 v[86:89], v[14:17], v[38:41], v[86:89]
	v_mfma_f32_16x16x32_bf16 v[62:65], v[14:17], v[30:33], v[62:65]
	v_mfma_f32_16x16x32_bf16 v[98:101], v[14:17], v[34:37], v[98:101]
	v_mfma_f32_16x16x32_bf16 v[102:105], v[14:17], v[22:25], v[102:105]
	v_add_u32_e32 v14, 0xf90, v141
	v_add_u32_e32 v15, 0xf94, v141
	ds_read2_b32 v[122:123], v14 offset1:1
	ds_read2_b32 v[124:125], v15 offset1:1
	ds_read_b128 v[14:17], v5 offset:768
	ds_read_b128 v[10:13], v5 offset:832
	v_mfma_f32_16x16x32_bf16 v[118:121], v[114:117], v[78:81], 0
	v_mfma_f32_16x16x32_bf16 v[106:109], v[114:117], v[70:73], v[106:109]
	v_mfma_f32_16x16x32_bf16 v[94:97], v[114:117], v[54:57], v[94:97]
	v_mfma_f32_16x16x32_bf16 v[90:93], v[114:117], v[58:61], v[90:93]
	v_mfma_f32_16x16x32_bf16 v[74:77], v[114:117], v[46:49], v[74:77]
	v_mfma_f32_16x16x32_bf16 v[66:69], v[114:117], v[42:45], v[66:69]
	v_mfma_f32_16x16x32_bf16 v[50:53], v[114:117], v[26:29], v[50:53]
	v_mfma_f32_16x16x32_bf16 v[82:85], v[114:117], v[38:41], v[82:85]
	v_mfma_f32_16x16x32_bf16 v[86:89], v[114:117], v[30:33], v[86:89]
	v_mfma_f32_16x16x32_bf16 v[62:65], v[114:117], v[34:37], v[62:65]
	v_mfma_f32_16x16x32_bf16 v[98:101], v[114:117], v[22:25], v[98:101]
	v_mfma_f32_16x16x32_bf16 v[102:105], v[114:117], v[18:21], v[102:105]
	s_waitcnt lgkmcnt(0)
	v_mfma_f32_16x16x32_bf16 v[110:113], v[114:117], v[14:17], v[110:113]
	v_add_u32_e32 v114, 0xf9c, v141
	ds_read2_b32 v[114:115], v114 offset1:1
	v_add_u32_e32 v116, 0xfd0, v141
	v_add_u32_e32 v117, 0xfd4, v141
	ds_read2_b32 v[126:127], v116 offset1:1
	ds_read2_b32 v[128:129], v117 offset1:1
	ds_read2_b32 v[166:167], v130 offset1:1
	s_waitcnt lgkmcnt(0)
	v_alignbit_b32 v117, v115, v114, v3
	v_alignbit_b32 v116, v114, v125, v4
	v_alignbit_b32 v115, v125, v123, v1
	v_alignbit_b32 v114, v124, v122, v2
	v_alignbit_b32 v169, v167, v166, v3
	v_alignbit_b32 v168, v166, v129, v4
	v_alignbit_b32 v167, v129, v127, v1
	v_alignbit_b32 v166, v128, v126, v2
	v_mfma_f32_16x16x32_bf16 v[122:125], v[114:117], v[78:81], 0
	v_mfma_f32_16x16x32_bf16 v[118:121], v[114:117], v[70:73], v[118:121]
	v_mfma_f32_16x16x32_bf16 v[106:109], v[114:117], v[54:57], v[106:109]
	v_mfma_f32_16x16x32_bf16 v[94:97], v[114:117], v[58:61], v[94:97]
	v_mfma_f32_16x16x32_bf16 v[90:93], v[114:117], v[46:49], v[90:93]
	v_mfma_f32_16x16x32_bf16 v[74:77], v[114:117], v[42:45], v[74:77]
	v_mfma_f32_16x16x32_bf16 v[66:69], v[114:117], v[26:29], v[66:69]
	v_mfma_f32_16x16x32_bf16 v[50:53], v[114:117], v[38:41], v[50:53]
	v_mfma_f32_16x16x32_bf16 v[82:85], v[114:117], v[30:33], v[82:85]
	v_mfma_f32_16x16x32_bf16 v[86:89], v[114:117], v[34:37], v[86:89]
	v_mfma_f32_16x16x32_bf16 v[62:65], v[114:117], v[22:25], v[62:65]
	v_mfma_f32_16x16x32_bf16 v[130:133], v[114:117], v[18:21], v[98:101]
	v_mfma_f32_16x16x32_bf16 v[134:137], v[114:117], v[14:17], v[102:105]
	v_mfma_f32_16x16x32_bf16 v[162:165], v[114:117], v[10:13], v[110:113]
	v_mfma_f32_16x16x32_bf16 v[126:129], v[166:169], v[78:81], 0
	v_mfma_f32_16x16x32_bf16 v[122:125], v[166:169], v[70:73], v[122:125]
	v_mfma_f32_16x16x32_bf16 v[118:121], v[166:169], v[54:57], v[118:121]
	v_mfma_f32_16x16x32_bf16 v[114:117], v[166:169], v[58:61], v[106:109]
	v_mfma_f32_16x16x32_bf16 v[110:113], v[166:169], v[46:49], v[94:97]
	v_mfma_f32_16x16x32_bf16 v[106:109], v[166:169], v[42:45], v[90:93]
	v_mfma_f32_16x16x32_bf16 v[102:105], v[166:169], v[26:29], v[74:77]
	v_mfma_f32_16x16x32_bf16 v[98:101], v[166:169], v[38:41], v[66:69]
	v_mfma_f32_16x16x32_bf16 v[94:97], v[166:169], v[30:33], v[50:53]
	v_mfma_f32_16x16x32_bf16 v[90:93], v[166:169], v[34:37], v[82:85]
	v_mfma_f32_16x16x32_bf16 v[82:85], v[166:169], v[22:25], v[86:89]
	v_mfma_f32_16x16x32_bf16 v[74:77], v[166:169], v[18:21], v[62:65]
	s_nop 1
	v_mov_b32_e32 v86, v175
	v_mov_b32_e32 v87, v174
	v_mfma_f32_16x16x32_bf16 v[66:69], v[166:169], v[14:17], v[130:133]
	v_mfma_f32_16x16x32_bf16 v[50:53], v[166:169], v[10:13], v[134:137]
	s_nop 1
	v_mov_b32_e32 v130, 0
	v_mov_b32_e32 v131, v130
	v_mov_b32_e32 v132, v130
	v_mfma_f32_16x16x32_bf16 v[62:65], v[166:169], v[6:9], v[162:165]
	v_mov_b32_e32 v133, v130

.LBB0_2209:
	s_add_i32 s20, s12, 0x400
	s_ashr_i32 s20, s20, 3
	s_ashr_i32 s21, s20, 31
	s_lshl_b64 s[20:21], s[20:21], 7
	s_and_b32 s32, s12, 7
	v_mov_b32_e32 v244, s32
	v_or3_b32 v244, s20, v140, v244
	v_mov_b32_e32 v245, s21
	v_lshlrev_b64 v[244:245], 12, v[244:245]
	v_lshl_add_u64 v[244:245], v[160:161], 0, v[244:245]
	global_load_dword v233, v[244:245], off
	global_load_dword v233, v[244:245], off offset:64
	global_load_dword v233, v[244:245], off offset:128
	global_load_dword v233, v[244:245], off offset:192
	global_load_dword v233, v[244:245], off offset:256
	global_load_dword v233, v[244:245], off offset:320
	global_load_dword v233, v[244:245], off offset:384
	global_load_dword v233, v[244:245], off offset:448
	global_load_dword v233, v[244:245], off offset:512
	global_load_dword v233, v[244:245], off offset:576
	global_load_dword v233, v[244:245], off offset:640
	global_load_dword v233, v[244:245], off offset:704
	global_load_dword v233, v[244:245], off offset:768
	global_load_dword v233, v[244:245], off offset:832
	global_load_dword v233, v[244:245], off offset:896
	global_load_dword v233, v[244:245], off offset:960
	s_cmp_lt_u32 s88, 4
	s_cbranch_scc1 .Lp7_nostag1
	s_sleep 4
